# first seam uses the XCD-hierarchical barrier instead of cooperative-groups grid.sync
# speedup vs baseline: 1.0018x; 1.0018x over previous
; #define LAS __attribute__((address_space(3)))
; DI unsigned xb_xcc_id() { return (unsigned)__builtin_amdgcn_s_getreg((3 << 11) | 20) & 0xFu; }
; DI void xcd_barrier(unsigned* bar, volatile LAS unsigned* st, int wv) {
;   asm volatile("s_waitcnt vmcnt(0)" ::: "memory");
;   __syncthreads();
;   if (xb_leader_lane(wv)) {
;     __builtin_amdgcn_s_waitcnt(0);
;     const unsigned x = xb_xcc_id();
;     unsigned nloc = st[0], nx = st[1];
;     if (nloc == 0u) { xcd_barrier_complete(bar, x, nloc, nx); st[0] = nloc; st[1] = nx; }
; __global__ void __launch_bounds__(512, 1) mega_kernel(Params p) {
;     ...
;   for (int ph = p.phase_lo; ph <= p.phase_hi; ++ph) {
;     if (ph == p.phase_lo + 1) grid.sync();
;     else if (ph > p.phase_lo + 1) xcd_barrier(p.bar, xb_st, wv);
.LBB0_6:
	v_readlane_b32 s2, v253, 38
	s_mov_b64 s[0:1], 0
	s_cmp_ge_i32 s26, s2
	s_mov_b64 s[2:3], 0
	s_cbranch_scc0 .LBB0_61
	s_waitcnt vmcnt(0)
	v_readlane_b32 s2, v253, 3
	s_barrier
	v_mbcnt_lo_u32_b32 v0, -1, 0
	v_mbcnt_hi_u32_b32 v0, -1, v0
	v_readlane_b32 s3, v253, 4
	v_cmp_eq_u32_e32 vcc, 0, v0
	s_and_b64 s[4:5], s[2:3], vcc
	s_and_saveexec_b64 s[2:3], s[4:5]
	s_cbranch_execz .LBB0_60
	v_mov_b32_e32 v0, 0x24008
	s_waitcnt vmcnt(0) expcnt(0) lgkmcnt(0)
	s_getreg_b32 s4, hwreg(HW_REG_XCC_ID, 0, 4)
	ds_read_b32 v3, v0
	v_mov_b32_e32 v0, 0x2400c
	ds_read_b32 v2, v0
	s_and_b32 s10, s4, 15
	s_waitcnt lgkmcnt(1)
	v_cmp_ne_u32_e32 vcc, 0, v3
	s_cbranch_vccnz .LBB0_24
	s_mov_b32 s11, 1
	s_branch .LBB0_12

; __global__ void __launch_bounds__(512, 1) mega_kernel(Params p) {
;     ...
;   for (int ph = p.phase_lo; ph <= p.phase_hi; ++ph) {
;     if (ph == p.phase_lo + 1) grid.sync();
;     else if (ph > p.phase_lo + 1) xcd_barrier(p.bar, xb_st, wv);
.LBB0_61:
.LBB0_73:
	s_and_b64 vcc, exec, s[2:3]
	s_cbranch_vccz .LBB0_75
